# att Q/V tile loads, m3 V tile loads, m1 K tile loads issued in batches before their LDS writes (on top of merged stages 2+3)
# baseline (speedup 1.0000x reference)
.LBB0_634:
	v_and_b32_e32 v12, 0x7e, v1
	v_ashrrev_i32_e32 v13, 3, v0
	v_mul_u32_u24_e32 v96, 0x3600, v12
	v_and_b32_e32 v10, -8, v13
	v_lshl_add_u64 v[2:3], s[6:7], 0, v[96:97]
	v_ashrrev_i32_e32 v11, 31, v10
	v_lshl_add_u64 v[6:7], v[10:11], 1, v[2:3]
	global_load_dwordx4 v[2:5], v[6:7], off offset:3072
	v_add_co_u32_e32 v6, vcc, s8, v6
	v_lshl_add_u32 v12, v12, 1, 0
	s_nop 0
	v_addc_co_u32_e32 v7, vcc, 0, v7, vcc
	s_waitcnt lgkmcnt(8)
	global_load_dwordx4 v[6:9], v[6:7], off offset:512
	v_add_u32_e32 v16, 0x100, v0
	v_add_u32_e32 v17, 0x200, v1
	v_and_b32_e32 v28, 0x7e, v17
	v_ashrrev_i32_e32 v29, 3, v16
	v_mul_u32_u24_e32 v96, 0x3600, v28
	v_and_b32_e32 v26, -8, v29
	v_lshl_add_u64 v[18:19], s[6:7], 0, v[96:97]
	v_ashrrev_i32_e32 v27, 31, v26
	v_lshl_add_u64 v[22:23], v[26:27], 1, v[18:19]
	global_load_dwordx4 v[18:21], v[22:23], off offset:3072
	v_add_co_u32_e32 v22, vcc, s8, v22
	v_lshl_add_u32 v28, v28, 1, 0
	s_nop 0
	v_addc_co_u32_e32 v23, vcc, 0, v23, vcc
	s_waitcnt lgkmcnt(8)
	global_load_dwordx4 v[22:25], v[22:23], off offset:512
	v_add_u32_e32 v32, 0x200, v0
	v_add_u32_e32 v33, 0x400, v1
	v_and_b32_e32 v44, 0x7e, v33
	v_ashrrev_i32_e32 v45, 3, v32
	v_mul_u32_u24_e32 v96, 0x3600, v44
	v_and_b32_e32 v42, -8, v45
	v_lshl_add_u64 v[34:35], s[6:7], 0, v[96:97]
	v_ashrrev_i32_e32 v43, 31, v42
	v_lshl_add_u64 v[38:39], v[42:43], 1, v[34:35]
	global_load_dwordx4 v[34:37], v[38:39], off offset:3072
	v_add_co_u32_e32 v38, vcc, s8, v38
	v_lshl_add_u32 v44, v44, 1, 0
	s_nop 0
	v_addc_co_u32_e32 v39, vcc, 0, v39, vcc
	s_waitcnt lgkmcnt(8)
	global_load_dwordx4 v[38:41], v[38:39], off offset:512
	v_add_u32_e32 v48, 0x300, v0
	v_add_u32_e32 v49, 0x600, v1
	v_and_b32_e32 v60, 0x7e, v49
	v_ashrrev_i32_e32 v61, 3, v48
	v_mul_u32_u24_e32 v96, 0x3600, v60
	v_and_b32_e32 v58, -8, v61
	v_lshl_add_u64 v[50:51], s[6:7], 0, v[96:97]
	v_ashrrev_i32_e32 v59, 31, v58
	v_lshl_add_u64 v[54:55], v[58:59], 1, v[50:51]
	global_load_dwordx4 v[50:53], v[54:55], off offset:3072
	v_add_co_u32_e32 v54, vcc, s8, v54
	v_lshl_add_u32 v60, v60, 1, 0
	s_nop 0
	v_addc_co_u32_e32 v55, vcc, 0, v55, vcc
	s_waitcnt lgkmcnt(8)
	global_load_dwordx4 v[54:57], v[54:55], off offset:512
	s_waitcnt vmcnt(7)
	v_and_b32_e32 v11, 0xffff, v2
	v_lshrrev_b32_e32 v2, 16, v2
	s_waitcnt vmcnt(6)
	v_lshl_or_b32 v14, v6, 16, v11
	v_mad_u64_u32 v[10:11], s[38:39], v10, s87, v[12:13]
	v_and_or_b32 v2, v6, s79, v2
	v_add_u32_e32 v6, 0x8800, v10
	ds_write2_b32 v6, v14, v2 offset1:68
	v_and_b32_e32 v2, 0xffff, v3
	v_lshrrev_b32_e32 v3, 16, v3
	v_lshl_or_b32 v2, v7, 16, v2
	v_and_or_b32 v3, v7, s79, v3
	ds_write2_b32 v6, v2, v3 offset0:136 offset1:204
	v_and_b32_e32 v2, 0xffff, v4
	v_lshrrev_b32_e32 v3, 16, v4
	v_lshl_or_b32 v2, v8, 16, v2
	v_and_or_b32 v3, v8, s79, v3
	v_add_u32_e32 v4, 0x8c00, v10
	ds_write2_b32 v4, v2, v3 offset0:16 offset1:84
	v_and_b32_e32 v2, 0xffff, v5
	v_lshl_or_b32 v2, v9, 16, v2
	ds_write_b32 v10, v2 offset:36448
	v_lshrrev_b32_e32 v2, 16, v5
	v_and_or_b32 v4, v9, s79, v2
	v_or_b32_e32 v2, 7, v13
	v_mad_u64_u32 v[2:3], s[38:39], v2, s87, v[12:13]
	ds_write_b32 v2, v4 offset:34816
	s_waitcnt vmcnt(5)
	v_and_b32_e32 v27, 0xffff, v18
	v_lshrrev_b32_e32 v18, 16, v18
	s_waitcnt vmcnt(4)
	v_lshl_or_b32 v30, v22, 16, v27
	v_mad_u64_u32 v[26:27], s[38:39], v26, s87, v[28:29]
	v_and_or_b32 v18, v22, s79, v18
	v_add_u32_e32 v22, 0x8800, v26
	ds_write2_b32 v22, v30, v18 offset1:68
	v_and_b32_e32 v18, 0xffff, v19
	v_lshrrev_b32_e32 v19, 16, v19
	v_lshl_or_b32 v18, v23, 16, v18
	v_and_or_b32 v19, v23, s79, v19
	ds_write2_b32 v22, v18, v19 offset0:136 offset1:204
	v_and_b32_e32 v18, 0xffff, v20
	v_lshrrev_b32_e32 v19, 16, v20
	v_lshl_or_b32 v18, v24, 16, v18
	v_and_or_b32 v19, v24, s79, v19
	v_add_u32_e32 v20, 0x8c00, v26
	ds_write2_b32 v20, v18, v19 offset0:16 offset1:84
	v_and_b32_e32 v18, 0xffff, v21
	v_lshl_or_b32 v18, v25, 16, v18
	ds_write_b32 v26, v18 offset:36448
	v_lshrrev_b32_e32 v18, 16, v21
	v_and_or_b32 v20, v25, s79, v18
	v_or_b32_e32 v18, 7, v29
	v_mad_u64_u32 v[18:19], s[38:39], v18, s87, v[28:29]
	ds_write_b32 v18, v20 offset:34816
	s_waitcnt vmcnt(3)
	v_and_b32_e32 v43, 0xffff, v34
	v_lshrrev_b32_e32 v34, 16, v34
	s_waitcnt vmcnt(2)
	v_lshl_or_b32 v46, v38, 16, v43
	v_mad_u64_u32 v[42:43], s[38:39], v42, s87, v[44:45]
	v_and_or_b32 v34, v38, s79, v34
	v_add_u32_e32 v38, 0x8800, v42
	ds_write2_b32 v38, v46, v34 offset1:68
	v_and_b32_e32 v34, 0xffff, v35
	v_lshrrev_b32_e32 v35, 16, v35
	v_lshl_or_b32 v34, v39, 16, v34
	v_and_or_b32 v35, v39, s79, v35
	ds_write2_b32 v38, v34, v35 offset0:136 offset1:204
	v_and_b32_e32 v34, 0xffff, v36
	v_lshrrev_b32_e32 v35, 16, v36
	v_lshl_or_b32 v34, v40, 16, v34
	v_and_or_b32 v35, v40, s79, v35
	v_add_u32_e32 v36, 0x8c00, v42
	ds_write2_b32 v36, v34, v35 offset0:16 offset1:84
	v_and_b32_e32 v34, 0xffff, v37
	v_lshl_or_b32 v34, v41, 16, v34
	ds_write_b32 v42, v34 offset:36448
	v_lshrrev_b32_e32 v34, 16, v37
	v_and_or_b32 v36, v41, s79, v34
	v_or_b32_e32 v34, 7, v45
	v_mad_u64_u32 v[34:35], s[38:39], v34, s87, v[44:45]
	ds_write_b32 v34, v36 offset:34816
	s_waitcnt vmcnt(1)
	v_and_b32_e32 v59, 0xffff, v50
	v_lshrrev_b32_e32 v50, 16, v50
	s_waitcnt vmcnt(0)
	v_lshl_or_b32 v62, v54, 16, v59
	v_mad_u64_u32 v[58:59], s[38:39], v58, s87, v[60:61]
	v_and_or_b32 v50, v54, s79, v50
	v_add_u32_e32 v54, 0x8800, v58
	ds_write2_b32 v54, v62, v50 offset1:68
	v_and_b32_e32 v50, 0xffff, v51
	v_lshrrev_b32_e32 v51, 16, v51
	v_lshl_or_b32 v50, v55, 16, v50
	v_and_or_b32 v51, v55, s79, v51
	ds_write2_b32 v54, v50, v51 offset0:136 offset1:204
	v_and_b32_e32 v50, 0xffff, v52
	v_lshrrev_b32_e32 v51, 16, v52
	v_lshl_or_b32 v50, v56, 16, v50
	v_and_or_b32 v51, v56, s79, v51
	v_add_u32_e32 v52, 0x8c00, v58
	ds_write2_b32 v52, v50, v51 offset0:16 offset1:84
	v_and_b32_e32 v50, 0xffff, v53
	v_lshl_or_b32 v50, v57, 16, v50
	ds_write_b32 v58, v50 offset:36448
	v_lshrrev_b32_e32 v50, 16, v53
	v_and_or_b32 v52, v57, s79, v50
	v_or_b32_e32 v50, 7, v61
	v_mad_u64_u32 v[50:51], s[38:39], v50, s87, v[60:61]
	ds_write_b32 v50, v52 offset:34816
	s_mov_b64 s[12:13], exec

.LBB0_703:
	v_ashrrev_i32_e32 v4, 31, v1
	v_lshrrev_b32_e32 v4, 29, v4
	v_add_u32_e32 v4, v1, v4
	v_ashrrev_i32_e32 v8, 3, v4
	v_ashrrev_i32_e32 v9, 31, v8
	v_lshlrev_b32_e32 v6, 6, v8
	v_lshlrev_b64 v[4:5], 10, v[8:9]
	v_sub_u32_e32 v6, v3, v6
	v_lshl_add_u64 v[4:5], s[2:3], 0, v[4:5]
	v_ashrrev_i32_e32 v7, 31, v6
	v_lshl_add_u64 v[4:5], v[6:7], 1, v[4:5]
	global_load_dwordx4 v[10:13], v[4:5], off
	v_add_u32_e32 v9, 0x100, v1
	v_cmp_lt_i32_e32 vcc, s80, v1
	s_or_b64 s[6:7], vcc, s[6:7]
	v_mov_b32_e32 v1, v9
	v_lshl_add_u32 v8, v8, 4, v2
	v_add_u32_e32 v2, 0x1000, v2
	v_add_u32_e32 v3, 0x800, v3
	v_mov_b32_e32 v22, v8
	v_ashrrev_i32_e32 v4, 31, v1
	v_lshrrev_b32_e32 v4, 29, v4
	v_add_u32_e32 v4, v1, v4
	v_ashrrev_i32_e32 v8, 3, v4
	v_ashrrev_i32_e32 v9, 31, v8
	v_lshlrev_b32_e32 v6, 6, v8
	v_lshlrev_b64 v[4:5], 10, v[8:9]
	v_sub_u32_e32 v6, v3, v6
	v_lshl_add_u64 v[4:5], s[2:3], 0, v[4:5]
	v_ashrrev_i32_e32 v7, 31, v6
	v_lshl_add_u64 v[4:5], v[6:7], 1, v[4:5]
	global_load_dwordx4 v[14:17], v[4:5], off
	v_add_u32_e32 v9, 0x100, v1
	v_cmp_lt_i32_e32 vcc, s80, v1
	s_or_b64 s[6:7], vcc, s[6:7]
	v_mov_b32_e32 v1, v9
	v_lshl_add_u32 v8, v8, 4, v2
	v_add_u32_e32 v2, 0x1000, v2
	v_add_u32_e32 v3, 0x800, v3
	v_mov_b32_e32 v23, v8
	v_ashrrev_i32_e32 v4, 31, v1
	v_lshrrev_b32_e32 v4, 29, v4
	v_add_u32_e32 v4, v1, v4
	v_ashrrev_i32_e32 v8, 3, v4
	v_ashrrev_i32_e32 v9, 31, v8
	v_lshlrev_b32_e32 v6, 6, v8
	v_lshlrev_b64 v[4:5], 10, v[8:9]
	v_sub_u32_e32 v6, v3, v6
	v_lshl_add_u64 v[4:5], s[2:3], 0, v[4:5]
	v_ashrrev_i32_e32 v7, 31, v6
	v_lshl_add_u64 v[4:5], v[6:7], 1, v[4:5]
	global_load_dwordx4 v[18:21], v[4:5], off
	v_add_u32_e32 v9, 0x100, v1
	v_cmp_lt_i32_e32 vcc, s80, v1
	s_or_b64 s[6:7], vcc, s[6:7]
	v_mov_b32_e32 v1, v9
	v_lshl_add_u32 v8, v8, 4, v2
	v_add_u32_e32 v2, 0x1000, v2
	v_add_u32_e32 v3, 0x800, v3
	v_mov_b32_e32 v24, v8
	v_ashrrev_i32_e32 v4, 31, v1
	v_lshrrev_b32_e32 v4, 29, v4
	v_add_u32_e32 v4, v1, v4
	v_ashrrev_i32_e32 v8, 3, v4
	v_ashrrev_i32_e32 v9, 31, v8
	v_lshlrev_b32_e32 v6, 6, v8
	v_lshlrev_b64 v[4:5], 10, v[8:9]
	v_sub_u32_e32 v6, v3, v6
	v_lshl_add_u64 v[4:5], s[2:3], 0, v[4:5]
	v_ashrrev_i32_e32 v7, 31, v6
	v_lshl_add_u64 v[4:5], v[6:7], 1, v[4:5]
	global_load_dwordx4 v[4:7], v[4:5], off
	v_add_u32_e32 v9, 0x100, v1
	v_cmp_lt_i32_e32 vcc, s80, v1
	s_or_b64 s[6:7], vcc, s[6:7]
	v_mov_b32_e32 v1, v9
	v_lshl_add_u32 v8, v8, 4, v2
	v_add_u32_e32 v2, 0x1000, v2
	v_add_u32_e32 v3, 0x800, v3
	s_waitcnt vmcnt(3)
	ds_write_b128 v22, v[10:13]
	s_waitcnt vmcnt(2)
	ds_write_b128 v23, v[14:17]
	s_waitcnt vmcnt(1)
	ds_write_b128 v24, v[18:21]
	s_waitcnt vmcnt(0)
	ds_write_b128 v8, v[4:7]

.LBB0_716:
	v_bfe_u32 v35, v32, 5, 1
	v_lshl_or_b32 v36, v35, 6, v33
	v_mul_u32_u24_e32 v36, 0x1b00, v36
	v_ashrrev_i32_e32 v47, 3, v32
	v_lshlrev_b32_e32 v96, 1, v36
	v_and_b32_e32 v44, -8, v47
	v_lshl_add_u64 v[36:37], s[12:13], 0, v[96:97]
	v_ashrrev_i32_e32 v45, 31, v44
	v_lshl_add_u64 v[40:41], v[44:45], 1, v[36:37]
	global_load_dwordx4 v[36:39], v[40:41], off
	v_add_co_u32_e32 v40, vcc, s85, v40
	v_lshl_add_u32 v46, v35, 2, v34
	s_nop 0
	v_addc_co_u32_e32 v41, vcc, 0, v41, vcc
	global_load_dwordx4 v[40:43], v[40:41], off
	v_mad_u64_u32 v[44:45], s[40:41], v44, s87, v[46:47]
	v_add_u32_e32 v71, 0x100, v32
	v_bfe_u32 v72, v71, 5, 1
	v_lshl_or_b32 v74, v72, 6, v33
	v_mul_u32_u24_e32 v74, 0x1b00, v74
	v_ashrrev_i32_e32 v85, 3, v71
	v_lshlrev_b32_e32 v96, 1, v74
	v_and_b32_e32 v82, -8, v85
	v_lshl_add_u64 v[74:75], s[12:13], 0, v[96:97]
	v_ashrrev_i32_e32 v83, 31, v82
	v_lshl_add_u64 v[78:79], v[82:83], 1, v[74:75]
	global_load_dwordx4 v[74:77], v[78:79], off
	v_add_co_u32_e32 v78, vcc, s85, v78
	v_lshl_add_u32 v84, v72, 2, v34
	s_nop 0
	v_addc_co_u32_e32 v79, vcc, 0, v79, vcc
	global_load_dwordx4 v[78:81], v[78:79], off
	v_mad_u64_u32 v[82:83], s[40:41], v82, s87, v[84:85]
	s_waitcnt vmcnt(3)
	v_and_b32_e32 v35, 0xffff, v36
	v_lshrrev_b32_e32 v36, 16, v36
	s_waitcnt vmcnt(2)
	v_lshl_or_b32 v35, v40, 16, v35
	v_and_or_b32 v36, v40, s79, v36
	v_add_u32_e32 v40, 0x4800, v44
	ds_write2_b32 v40, v35, v36 offset1:68
	v_and_b32_e32 v35, 0xffff, v37
	v_lshrrev_b32_e32 v36, 16, v37
	v_lshl_or_b32 v35, v41, 16, v35
	v_and_or_b32 v36, v41, s79, v36
	ds_write2_b32 v40, v35, v36 offset0:136 offset1:204
	v_and_b32_e32 v35, 0xffff, v38
	v_lshrrev_b32_e32 v36, 16, v38
	v_lshl_or_b32 v35, v42, 16, v35
	v_and_or_b32 v36, v42, s79, v36
	v_add_u32_e32 v37, 0x4c00, v44
	ds_write2_b32 v37, v35, v36 offset0:16 offset1:84
	v_and_b32_e32 v35, 0xffff, v39
	v_lshl_or_b32 v35, v43, 16, v35
	v_or_b32_e32 v36, 7, v47
	ds_write_b32 v44, v35 offset:20064
	v_lshrrev_b32_e32 v35, 16, v39
	v_mad_u64_u32 v[36:37], s[40:41], v36, s87, v[46:47]
	v_and_or_b32 v35, v43, s79, v35
	s_movk_i32 s40, 0xff
	ds_write_b32 v36, v35 offset:18432
	s_waitcnt vmcnt(1)
	v_and_b32_e32 v72, 0xffff, v74
	v_lshrrev_b32_e32 v74, 16, v74
	s_waitcnt vmcnt(0)
	v_lshl_or_b32 v72, v78, 16, v72
	v_and_or_b32 v74, v78, s79, v74
	v_add_u32_e32 v78, 0x4800, v82
	ds_write2_b32 v78, v72, v74 offset1:68
	v_and_b32_e32 v72, 0xffff, v75
	v_lshrrev_b32_e32 v74, 16, v75
	v_lshl_or_b32 v72, v79, 16, v72
	v_and_or_b32 v74, v79, s79, v74
	ds_write2_b32 v78, v72, v74 offset0:136 offset1:204
	v_and_b32_e32 v72, 0xffff, v76
	v_lshrrev_b32_e32 v74, 16, v76
	v_lshl_or_b32 v72, v80, 16, v72
	v_and_or_b32 v74, v80, s79, v74
	v_add_u32_e32 v75, 0x4c00, v82
	ds_write2_b32 v75, v72, v74 offset0:16 offset1:84
	v_and_b32_e32 v72, 0xffff, v77
	v_lshl_or_b32 v72, v81, 16, v72
	v_or_b32_e32 v74, 7, v85
	ds_write_b32 v82, v72 offset:20064
	v_lshrrev_b32_e32 v72, 16, v77
	v_mad_u64_u32 v[74:75], s[40:41], v74, s87, v[84:85]
	v_and_or_b32 v72, v81, s79, v72
	s_movk_i32 s40, 0xff
	ds_write_b32 v74, v72 offset:18432
	s_mov_b64 s[38:39], exec

.LBB0_1105:
	v_mov_b32_e32 v233, 0
	v_bfe_u32 v121, v119, 5, 1
	v_lshl_or_b32 v96, v121, 6, v118
	v_mul_u32_u24_e32 v96, 0x1b00, v96
	v_ashrrev_i32_e32 v238, 3, v119
	v_lshlrev_b32_e32 v96, 1, v96
	v_and_b32_e32 v126, -8, v238
	v_lshl_add_u64 v[122:123], s[2:3], 0, v[96:97]
	v_ashrrev_i32_e32 v127, 31, v126
	v_lshl_add_u64 v[234:235], v[126:127], 1, v[122:123]
	global_load_dwordx4 v[122:125], v[234:235], off
	v_add_co_u32_e32 v234, vcc, s85, v234
	v_lshl_add_u32 v96, v121, 2, v120
	s_nop 0
	v_addc_co_u32_e32 v235, vcc, 0, v235, vcc
	global_load_dwordx4 v[234:237], v[234:235], off
	v_mad_u64_u32 v[126:127], s[12:13], v126, s87, v[96:97]
	v_add_u32_e32 v229, 0x100, v119
	v_bfe_u32 v230, v229, 5, 1
	v_lshl_or_b32 v232, v230, 6, v118
	v_mul_u32_u24_e32 v232, 0x1b00, v232
	v_ashrrev_i32_e32 v239, 3, v229
	v_lshlrev_b32_e32 v232, 1, v232
	v_and_b32_e32 v246, -8, v239
	v_lshl_add_u64 v[242:243], s[2:3], 0, v[232:233]
	v_ashrrev_i32_e32 v247, 31, v246
	v_lshl_add_u64 v[252:253], v[246:247], 1, v[242:243]
	global_load_dwordx4 v[242:245], v[252:253], off
	v_add_co_u32_e32 v252, vcc, s85, v252
	v_lshl_add_u32 v232, v230, 2, v120
	s_nop 0
	v_addc_co_u32_e32 v253, vcc, 0, v253, vcc
	global_load_dwordx4 v[252:255], v[252:253], off
	v_mad_u64_u32 v[246:247], s[12:13], v246, s87, v[232:233]
	s_waitcnt vmcnt(3)
	v_and_b32_e32 v121, 0xffff, v122
	v_lshrrev_b32_e32 v122, 16, v122
	s_waitcnt vmcnt(2)
	v_lshl_or_b32 v121, v234, 16, v121
	v_and_or_b32 v122, v234, s79, v122
	ds_write2_b32 v126, v121, v122 offset1:68
	v_and_b32_e32 v121, 0xffff, v123
	v_lshrrev_b32_e32 v122, 16, v123
	v_lshl_or_b32 v121, v235, 16, v121
	v_and_or_b32 v122, v235, s79, v122
	ds_write2_b32 v126, v121, v122 offset0:136 offset1:204
	v_and_b32_e32 v121, 0xffff, v124
	v_lshrrev_b32_e32 v122, 16, v124
	v_lshl_or_b32 v121, v236, 16, v121
	v_and_or_b32 v122, v236, s79, v122
	v_add_u32_e32 v123, 0x400, v126
	ds_write2_b32 v123, v121, v122 offset0:16 offset1:84
	v_and_b32_e32 v121, 0xffff, v125
	v_lshl_or_b32 v121, v237, 16, v121
	v_or_b32_e32 v122, 7, v238
	ds_write_b32 v126, v121 offset:1632
	v_lshrrev_b32_e32 v121, 16, v125
	v_mad_u64_u32 v[122:123], s[12:13], v122, s87, v[96:97]
	v_and_or_b32 v121, v237, s79, v121
	ds_write_b32 v122, v121
	s_waitcnt vmcnt(1)
	v_and_b32_e32 v230, 0xffff, v242
	v_lshrrev_b32_e32 v242, 16, v242
	s_waitcnt vmcnt(0)
	v_lshl_or_b32 v230, v252, 16, v230
	v_and_or_b32 v242, v252, s79, v242
	ds_write2_b32 v246, v230, v242 offset1:68
	v_and_b32_e32 v230, 0xffff, v243
	v_lshrrev_b32_e32 v242, 16, v243
	v_lshl_or_b32 v230, v253, 16, v230
	v_and_or_b32 v242, v253, s79, v242
	ds_write2_b32 v246, v230, v242 offset0:136 offset1:204
	v_and_b32_e32 v230, 0xffff, v244
	v_lshrrev_b32_e32 v242, 16, v244
	v_lshl_or_b32 v230, v254, 16, v230
	v_and_or_b32 v242, v254, s79, v242
	v_add_u32_e32 v243, 0x400, v246
	ds_write2_b32 v243, v230, v242 offset0:16 offset1:84
	v_and_b32_e32 v230, 0xffff, v245
	v_lshl_or_b32 v230, v255, 16, v230
	v_or_b32_e32 v242, 7, v239
	ds_write_b32 v246, v230 offset:1632
	v_lshrrev_b32_e32 v230, 16, v245
	v_mad_u64_u32 v[242:243], s[12:13], v242, s87, v[232:233]
	v_and_or_b32 v230, v255, s79, v230
	ds_write_b32 v242, v230
	v_add_u32_e32 v119, 0x200, v119
	v_bfe_u32 v121, v119, 5, 1
	v_lshl_or_b32 v96, v121, 6, v118
	v_mul_u32_u24_e32 v96, 0x1b00, v96
	v_ashrrev_i32_e32 v238, 3, v119
	v_lshlrev_b32_e32 v96, 1, v96
	v_and_b32_e32 v126, -8, v238
	v_lshl_add_u64 v[122:123], s[2:3], 0, v[96:97]
	v_ashrrev_i32_e32 v127, 31, v126
	v_lshl_add_u64 v[234:235], v[126:127], 1, v[122:123]
	global_load_dwordx4 v[122:125], v[234:235], off
	v_add_co_u32_e32 v234, vcc, s85, v234
	v_lshl_add_u32 v96, v121, 2, v120
	s_nop 0
	v_addc_co_u32_e32 v235, vcc, 0, v235, vcc
	global_load_dwordx4 v[234:237], v[234:235], off
	v_mad_u64_u32 v[126:127], s[12:13], v126, s87, v[96:97]
	v_add_u32_e32 v229, 0x100, v119
	v_bfe_u32 v230, v229, 5, 1
	v_lshl_or_b32 v232, v230, 6, v118
	v_mul_u32_u24_e32 v232, 0x1b00, v232
	v_ashrrev_i32_e32 v239, 3, v229
	v_lshlrev_b32_e32 v232, 1, v232
	v_and_b32_e32 v246, -8, v239
	v_lshl_add_u64 v[242:243], s[2:3], 0, v[232:233]
	v_ashrrev_i32_e32 v247, 31, v246
	v_lshl_add_u64 v[252:253], v[246:247], 1, v[242:243]
	global_load_dwordx4 v[242:245], v[252:253], off
	v_add_co_u32_e32 v252, vcc, s85, v252
	v_lshl_add_u32 v232, v230, 2, v120
	s_nop 0
	v_addc_co_u32_e32 v253, vcc, 0, v253, vcc
	global_load_dwordx4 v[252:255], v[252:253], off
	v_mad_u64_u32 v[246:247], s[12:13], v246, s87, v[232:233]
	s_waitcnt vmcnt(3)
	v_and_b32_e32 v121, 0xffff, v122
	v_lshrrev_b32_e32 v122, 16, v122
	s_waitcnt vmcnt(2)
	v_lshl_or_b32 v121, v234, 16, v121
	v_and_or_b32 v122, v234, s79, v122
	ds_write2_b32 v126, v121, v122 offset1:68
	v_and_b32_e32 v121, 0xffff, v123
	v_lshrrev_b32_e32 v122, 16, v123
	v_lshl_or_b32 v121, v235, 16, v121
	v_and_or_b32 v122, v235, s79, v122
	ds_write2_b32 v126, v121, v122 offset0:136 offset1:204
	v_and_b32_e32 v121, 0xffff, v124
	v_lshrrev_b32_e32 v122, 16, v124
	v_lshl_or_b32 v121, v236, 16, v121
	v_and_or_b32 v122, v236, s79, v122
	v_add_u32_e32 v123, 0x400, v126
	ds_write2_b32 v123, v121, v122 offset0:16 offset1:84
	v_and_b32_e32 v121, 0xffff, v125
	v_lshl_or_b32 v121, v237, 16, v121
	v_or_b32_e32 v122, 7, v238
	ds_write_b32 v126, v121 offset:1632
	v_lshrrev_b32_e32 v121, 16, v125
	v_mad_u64_u32 v[122:123], s[12:13], v122, s87, v[96:97]
	v_and_or_b32 v121, v237, s79, v121
	ds_write_b32 v122, v121
	s_waitcnt vmcnt(1)
	v_and_b32_e32 v230, 0xffff, v242
	v_lshrrev_b32_e32 v242, 16, v242
	s_waitcnt vmcnt(0)
	v_lshl_or_b32 v230, v252, 16, v230
	v_and_or_b32 v242, v252, s79, v242
	ds_write2_b32 v246, v230, v242 offset1:68
	v_and_b32_e32 v230, 0xffff, v243
	v_lshrrev_b32_e32 v242, 16, v243
	v_lshl_or_b32 v230, v253, 16, v230
	v_and_or_b32 v242, v253, s79, v242
	ds_write2_b32 v246, v230, v242 offset0:136 offset1:204
	v_and_b32_e32 v230, 0xffff, v244
	v_lshrrev_b32_e32 v242, 16, v244
	v_lshl_or_b32 v230, v254, 16, v230
	v_and_or_b32 v242, v254, s79, v242
	v_add_u32_e32 v243, 0x400, v246
	ds_write2_b32 v243, v230, v242 offset0:16 offset1:84
	v_and_b32_e32 v230, 0xffff, v245
	v_lshl_or_b32 v230, v255, 16, v230
	v_or_b32_e32 v242, 7, v239
	ds_write_b32 v246, v230 offset:1632
	v_lshrrev_b32_e32 v230, 16, v245
	v_mad_u64_u32 v[242:243], s[12:13], v242, s87, v[232:233]
	v_and_or_b32 v230, v255, s79, v230
	ds_write_b32 v242, v230
	v_add_u32_e32 v119, 0x200, v119
	s_mov_b64 s[6:7], exec
